# prologue phase: W_up weight conversion rewritten by hand (all 5-6 tiles of a workgroup loaded up front, two alternating LDS transpose tiles, one barrier per tile)
# speedup vs baseline: 1.0081x; 1.0012x over previous
; DI int tid_now() { int t = threadIdx.x; asm volatile("" : "+v"(t)); return t; }
; DI unsigned pk2(float lo, float hi) { return (unsigned)f2bf(lo) | ((unsigned)f2bf(hi) << 16); }
;     DI bf16_t* z() const { return (bf16_t*)(ws + WS_Z); }
;     DI float* b1(int l, int v) const { return (float*)(ws + WS_B1) + (l * 2 + v) * 128; }
; template <class Map>
; DI void wconv(const float* __restrict__ W, int K, int Nsrc, const float* __restrict__ gain, bf16_t* __restrict__ dst, int Ndst, Map map, float* tile) {
;     const int nkt = K / 64, ntiles = nkt * (Ndst / 64); const int tid = tid_now();
;     const int kk0 = tid >> 4, nn4 = (tid & 15) * 4, nw = tid >> 3, cw = tid & 7;
;     int it = blockIdx.x; if (it >= ntiles) return;
;     f32x4 a0, a1, b0 = {0.f, 0.f, 0.f, 0.f}, b1 = {0.f, 0.f, 0.f, 0.f};
;     ...
;     WCONV_LOAD(it, a0, a1);
;     for (;;) {
;         const int nit = it + gridDim.x;
;         __syncthreads();
; #pragma unroll
;         for (int e = 0; e < 4; ++e) { tile[kk0 * 65 + nn4 + e] = a0[e]; tile[(kk0 + 32) * 65 + nn4 + e] = a1[e]; }
;         if (nit < ntiles) WCONV_LOAD(nit, b0, b1);
;         __syncthreads();
;         { const int kt = it % nkt, nt = it / nkt, k0 = kt * 64, n0 = nt * 64;
;           const float* tp = tile + (8 * cw) * 65 + nw;
;           u32x4 w; w.x = pk2(tp[0], tp[65]); w.y = pk2(tp[2 * 65], tp[3 * 65]); w.z = pk2(tp[4 * 65], tp[5 * 65]); w.w = pk2(tp[6 * 65], tp[7 * 65]);
;           *(u32x4*)(dst + (size_t)(n0 + nw) * K + k0 + 8 * cw) = w; }
;         if (nit >= ntiles) break;
;         a0 = b0; a1 = b1; it = nit;
;     }
.LBB0_2039:
	s_load_dwordx4 s[48:51], s[0:1], 0x70
	v_lshrrev_b32_e32 v4, 4, v214
	v_and_b32_e32 v5, 15, v214
	v_lshlrev_b32_e32 v5, 2, v5
	s_and_b32 s16, s2, 15
	s_lshl_b32 s16, s16, 6
	s_lshr_b32 s17, s2, 4
	s_lshr_b32 s22, s17, 2
	s_lshl_b32 s22, s22, 7
	s_and_b32 s23, s17, 3
	s_lshl_b32 s23, s23, 6
	s_add_i32 s22, s22, s23
	s_cmpk_gt_u32 s23, 0x7f
	s_cselect_b32 s24, 0xa80, 0
	s_add_i32 s22, s22, s24
	v_add_u32_e32 v6, s16, v4
	v_mul_u32_u24_e32 v7, 0x1600, v6
	v_add3_u32 v7, v7, s22, v5
	v_lshlrev_b32_e32 v7, 2, v7
	v_add_u32_e32 v11, 0xb0000, v7
	v_lshlrev_b32_e32 v8, 2, v6
	v_mul_u32_u24_e32 v12, 0x104, v4
	v_lshl_add_u32 v12, v5, 2, v12
	v_add_u32_e32 v12, 0x10000, v12
	v_add_u32_e32 v13, 0x2080, v12
	v_add_u32_e32 v14, 0x4100, v12
	v_add_u32_e32 v15, 0x4100, v13
	v_lshrrev_b32_e32 v20, 3, v214
	v_and_b32_e32 v21, 7, v214
	v_mul_u32_u24_e32 v16, 0x820, v21
	v_lshl_add_u32 v16, v20, 2, v16
	v_add_u32_e32 v16, 0x10000, v16
	v_add_u32_e32 v17, 0x410, v16
	v_add_u32_e32 v18, 0x4100, v16
	v_add_u32_e32 v19, 0x4100, v17
	s_lshl_b32 s23, s17, 6
	v_add_u32_e32 v22, s23, v20
	v_lshlrev_b32_e32 v22, 10, v22
	v_lshl_add_u32 v22, v21, 3, v22
	v_add_u32_e32 v22, s16, v22
	v_lshlrev_b32_e32 v22, 1, v22
	s_waitcnt lgkmcnt(0)
	s_mul_i32 s24, s54, 0x1600000
	s_add_u32 s42, s50, s24
	s_addc_u32 s43, s51, 0
	s_lshl_b32 s24, s54, 12
	s_add_u32 s50, s48, s24
	s_addc_u32 s51, s49, 0
	s_add_u32 s48, s52, 0x930000
	s_addc_u32 s49, s53, 0
	global_load_dword v9, v8, s[50:51]
	global_load_dword v10, v8, s[50:51] offset:128
	global_load_dwordx4 v[36:39], v7, s[42:43]
	global_load_dwordx4 v[40:43], v11, s[42:43]
	global_load_dwordx4 v[44:47], v7, s[42:43] offset:2048
	global_load_dwordx4 v[48:51], v11, s[42:43] offset:2048
	s_add_u32 s42, s42, 0x1000
	s_addc_u32 s43, s43, 0
	global_load_dwordx4 v[52:55], v7, s[42:43]
	global_load_dwordx4 v[56:59], v11, s[42:43]
	global_load_dwordx4 v[60:63], v7, s[42:43] offset:2048
	global_load_dwordx4 v[64:67], v11, s[42:43] offset:2048
	s_add_u32 s42, s42, 0x1000
	s_addc_u32 s43, s43, 0
	global_load_dwordx4 v[68:71], v7, s[42:43]
	global_load_dwordx4 v[72:75], v11, s[42:43]
	s_cmp_lt_u32 s2, 128
	s_cbranch_scc0 .Lwup_5
	global_load_dwordx4 v[76:79], v7, s[42:43] offset:2048
	global_load_dwordx4 v[80:83], v11, s[42:43] offset:2048
	s_add_u32 s42, s42, 0x1000
	s_addc_u32 s43, s43, 0
	s_waitcnt vmcnt(10)
	v_mul_f32_e32 v36, v36, v9
	v_mul_f32_e32 v37, v37, v9
	v_mul_f32_e32 v38, v38, v9
	v_mul_f32_e32 v39, v39, v9
	v_mul_f32_e32 v40, v40, v10
	v_mul_f32_e32 v41, v41, v10
	v_mul_f32_e32 v42, v42, v10
	v_mul_f32_e32 v43, v43, v10
	ds_write2_b32 v12, v36, v37 offset1:1
	ds_write2_b32 v12, v38, v39 offset0:2 offset1:3
	ds_write2_b32 v13, v40, v41 offset1:1
	ds_write2_b32 v13, v42, v43 offset0:2 offset1:3
	s_waitcnt lgkmcnt(0)
	s_barrier
	ds_read2_b32 v[24:25], v16 offset1:65
	ds_read2_b32 v[26:27], v16 offset0:130 offset1:195
	ds_read2_b32 v[84:85], v17 offset1:65
	ds_read2_b32 v[86:87], v17 offset0:130 offset1:195
	s_waitcnt lgkmcnt(0)
	v_cvt_pk_bf16_f32 v24, v24, v25
	v_cvt_pk_bf16_f32 v25, v26, v27
	v_cvt_pk_bf16_f32 v26, v84, v85
	v_cvt_pk_bf16_f32 v27, v86, v87
	global_store_dwordx4 v22, v[24:27], s[48:49]
	s_add_u32 s48, s48, 0x200000
	s_addc_u32 s49, s49, 0
	s_waitcnt vmcnt(9)
	v_mul_f32_e32 v44, v44, v9
	v_mul_f32_e32 v45, v45, v9
	v_mul_f32_e32 v46, v46, v9
	v_mul_f32_e32 v47, v47, v9
	v_mul_f32_e32 v48, v48, v10
	v_mul_f32_e32 v49, v49, v10
	v_mul_f32_e32 v50, v50, v10
	v_mul_f32_e32 v51, v51, v10
	ds_write2_b32 v14, v44, v45 offset1:1
	ds_write2_b32 v14, v46, v47 offset0:2 offset1:3
	ds_write2_b32 v15, v48, v49 offset1:1
	ds_write2_b32 v15, v50, v51 offset0:2 offset1:3
	s_waitcnt lgkmcnt(0)
	s_barrier
	ds_read2_b32 v[24:25], v18 offset1:65
	ds_read2_b32 v[26:27], v18 offset0:130 offset1:195
	ds_read2_b32 v[84:85], v19 offset1:65
	ds_read2_b32 v[86:87], v19 offset0:130 offset1:195
	s_waitcnt lgkmcnt(0)
	v_cvt_pk_bf16_f32 v24, v24, v25
	v_cvt_pk_bf16_f32 v25, v26, v27
	v_cvt_pk_bf16_f32 v26, v84, v85
	v_cvt_pk_bf16_f32 v27, v86, v87
	global_store_dwordx4 v22, v[24:27], s[48:49]
	s_add_u32 s48, s48, 0x200000
	s_addc_u32 s49, s49, 0
	s_waitcnt vmcnt(8)
	v_mul_f32_e32 v52, v52, v9
	v_mul_f32_e32 v53, v53, v9
	v_mul_f32_e32 v54, v54, v9
	v_mul_f32_e32 v55, v55, v9
	v_mul_f32_e32 v56, v56, v10
	v_mul_f32_e32 v57, v57, v10
	v_mul_f32_e32 v58, v58, v10
	v_mul_f32_e32 v59, v59, v10
	ds_write2_b32 v12, v52, v53 offset1:1
	ds_write2_b32 v12, v54, v55 offset0:2 offset1:3
	ds_write2_b32 v13, v56, v57 offset1:1
	ds_write2_b32 v13, v58, v59 offset0:2 offset1:3
	s_waitcnt lgkmcnt(0)
	s_barrier
	ds_read2_b32 v[24:25], v16 offset1:65
	ds_read2_b32 v[26:27], v16 offset0:130 offset1:195
	ds_read2_b32 v[84:85], v17 offset1:65
	ds_read2_b32 v[86:87], v17 offset0:130 offset1:195
	s_waitcnt lgkmcnt(0)
	v_cvt_pk_bf16_f32 v24, v24, v25
	v_cvt_pk_bf16_f32 v25, v26, v27
	v_cvt_pk_bf16_f32 v26, v84, v85
	v_cvt_pk_bf16_f32 v27, v86, v87
	global_store_dwordx4 v22, v[24:27], s[48:49]
	s_add_u32 s48, s48, 0x200000
	s_addc_u32 s49, s49, 0
	s_waitcnt vmcnt(7)
	v_mul_f32_e32 v60, v60, v9
	v_mul_f32_e32 v61, v61, v9
	v_mul_f32_e32 v62, v62, v9
	v_mul_f32_e32 v63, v63, v9
	v_mul_f32_e32 v64, v64, v10
	v_mul_f32_e32 v65, v65, v10
	v_mul_f32_e32 v66, v66, v10
	v_mul_f32_e32 v67, v67, v10
	ds_write2_b32 v14, v60, v61 offset1:1
	ds_write2_b32 v14, v62, v63 offset0:2 offset1:3
	ds_write2_b32 v15, v64, v65 offset1:1
	ds_write2_b32 v15, v66, v67 offset0:2 offset1:3
	s_waitcnt lgkmcnt(0)
	s_barrier
; DI unsigned pk2(float lo, float hi) { return (unsigned)f2bf(lo) | ((unsigned)f2bf(hi) << 16); }
;     DI bf16_t* z() const { return (bf16_t*)(ws + WS_Z); }
;     DI float* b1(int l, int v) const { return (float*)(ws + WS_B1) + (l * 2 + v) * 128; }
; template <class Map>
; DI void wconv(const float* __restrict__ W, int K, int Nsrc, const float* __restrict__ gain, bf16_t* __restrict__ dst, int Ndst, Map map, float* tile) {
;     ...
;     for (;;) {
;         const int nit = it + gridDim.x;
;         __syncthreads();
; #pragma unroll
;         for (int e = 0; e < 4; ++e) { tile[kk0 * 65 + nn4 + e] = a0[e]; tile[(kk0 + 32) * 65 + nn4 + e] = a1[e]; }
;         if (nit < ntiles) WCONV_LOAD(nit, b0, b1);
;         __syncthreads();
;         { const int kt = it % nkt, nt = it / nkt, k0 = kt * 64, n0 = nt * 64;
;           const float* tp = tile + (8 * cw) * 65 + nw;
;           u32x4 w; w.x = pk2(tp[0], tp[65]); w.y = pk2(tp[2 * 65], tp[3 * 65]); w.z = pk2(tp[4 * 65], tp[5 * 65]); w.w = pk2(tp[6 * 65], tp[7 * 65]);
;           *(u32x4*)(dst + (size_t)(n0 + nw) * K + k0 + 8 * cw) = w; }
;         if (nit >= ntiles) break;
;         a0 = b0; a1 = b1; it = nit;
;     }
	ds_read2_b32 v[24:25], v18 offset1:65
	ds_read2_b32 v[26:27], v18 offset0:130 offset1:195
	ds_read2_b32 v[84:85], v19 offset1:65
	ds_read2_b32 v[86:87], v19 offset0:130 offset1:195
	s_waitcnt lgkmcnt(0)
	v_cvt_pk_bf16_f32 v24, v24, v25
	v_cvt_pk_bf16_f32 v25, v26, v27
	v_cvt_pk_bf16_f32 v26, v84, v85
	v_cvt_pk_bf16_f32 v27, v86, v87
	global_store_dwordx4 v22, v[24:27], s[48:49]
	s_add_u32 s48, s48, 0x200000
	s_addc_u32 s49, s49, 0
	s_waitcnt vmcnt(6)
	v_mul_f32_e32 v68, v68, v9
	v_mul_f32_e32 v69, v69, v9
	v_mul_f32_e32 v70, v70, v9
	v_mul_f32_e32 v71, v71, v9
	v_mul_f32_e32 v72, v72, v10
	v_mul_f32_e32 v73, v73, v10
	v_mul_f32_e32 v74, v74, v10
	v_mul_f32_e32 v75, v75, v10
	ds_write2_b32 v12, v68, v69 offset1:1
	ds_write2_b32 v12, v70, v71 offset0:2 offset1:3
	ds_write2_b32 v13, v72, v73 offset1:1
	ds_write2_b32 v13, v74, v75 offset0:2 offset1:3
	s_waitcnt lgkmcnt(0)
	s_barrier
	ds_read2_b32 v[24:25], v16 offset1:65
	ds_read2_b32 v[26:27], v16 offset0:130 offset1:195
	ds_read2_b32 v[84:85], v17 offset1:65
	ds_read2_b32 v[86:87], v17 offset0:130 offset1:195
	s_waitcnt lgkmcnt(0)
	v_cvt_pk_bf16_f32 v24, v24, v25
	v_cvt_pk_bf16_f32 v25, v26, v27
	v_cvt_pk_bf16_f32 v26, v84, v85
	v_cvt_pk_bf16_f32 v27, v86, v87
	global_store_dwordx4 v22, v[24:27], s[48:49]
	s_add_u32 s48, s48, 0x200000
	s_addc_u32 s49, s49, 0
	s_waitcnt vmcnt(5)
	v_mul_f32_e32 v76, v76, v9
	v_mul_f32_e32 v77, v77, v9
	v_mul_f32_e32 v78, v78, v9
	v_mul_f32_e32 v79, v79, v9
	v_mul_f32_e32 v80, v80, v10
	v_mul_f32_e32 v81, v81, v10
	v_mul_f32_e32 v82, v82, v10
	v_mul_f32_e32 v83, v83, v10
	ds_write2_b32 v14, v76, v77 offset1:1
	ds_write2_b32 v14, v78, v79 offset0:2 offset1:3
	ds_write2_b32 v15, v80, v81 offset1:1
	ds_write2_b32 v15, v82, v83 offset0:2 offset1:3
	s_waitcnt lgkmcnt(0)
	s_barrier
	ds_read2_b32 v[24:25], v18 offset1:65
	ds_read2_b32 v[26:27], v18 offset0:130 offset1:195
	ds_read2_b32 v[84:85], v19 offset1:65
	ds_read2_b32 v[86:87], v19 offset0:130 offset1:195
	s_waitcnt lgkmcnt(0)
	v_cvt_pk_bf16_f32 v24, v24, v25
	v_cvt_pk_bf16_f32 v25, v26, v27
	v_cvt_pk_bf16_f32 v26, v84, v85
	v_cvt_pk_bf16_f32 v27, v86, v87
	global_store_dwordx4 v22, v[24:27], s[48:49]
	s_branch .Lwup_done
.Lwup_5:
	s_waitcnt vmcnt(8)
	v_mul_f32_e32 v36, v36, v9
	v_mul_f32_e32 v37, v37, v9
	v_mul_f32_e32 v38, v38, v9
	v_mul_f32_e32 v39, v39, v9
	v_mul_f32_e32 v40, v40, v10
	v_mul_f32_e32 v41, v41, v10
	v_mul_f32_e32 v42, v42, v10
	v_mul_f32_e32 v43, v43, v10
	ds_write2_b32 v12, v36, v37 offset1:1
	ds_write2_b32 v12, v38, v39 offset0:2 offset1:3
	ds_write2_b32 v13, v40, v41 offset1:1
	ds_write2_b32 v13, v42, v43 offset0:2 offset1:3
	s_waitcnt lgkmcnt(0)
	s_barrier
	ds_read2_b32 v[24:25], v16 offset1:65
	ds_read2_b32 v[26:27], v16 offset0:130 offset1:195
	ds_read2_b32 v[84:85], v17 offset1:65
	ds_read2_b32 v[86:87], v17 offset0:130 offset1:195
	s_waitcnt lgkmcnt(0)
	v_cvt_pk_bf16_f32 v24, v24, v25
	v_cvt_pk_bf16_f32 v25, v26, v27
	v_cvt_pk_bf16_f32 v26, v84, v85
	v_cvt_pk_bf16_f32 v27, v86, v87
	global_store_dwordx4 v22, v[24:27], s[48:49]
	s_add_u32 s48, s48, 0x200000
	s_addc_u32 s49, s49, 0
	s_waitcnt vmcnt(7)
	v_mul_f32_e32 v44, v44, v9
	v_mul_f32_e32 v45, v45, v9
	v_mul_f32_e32 v46, v46, v9
	v_mul_f32_e32 v47, v47, v9
	v_mul_f32_e32 v48, v48, v10
	v_mul_f32_e32 v49, v49, v10
	v_mul_f32_e32 v50, v50, v10
	v_mul_f32_e32 v51, v51, v10
	ds_write2_b32 v14, v44, v45 offset1:1
	ds_write2_b32 v14, v46, v47 offset0:2 offset1:3
	ds_write2_b32 v15, v48, v49 offset1:1
	ds_write2_b32 v15, v50, v51 offset0:2 offset1:3
	s_waitcnt lgkmcnt(0)
	s_barrier
	ds_read2_b32 v[24:25], v18 offset1:65
	ds_read2_b32 v[26:27], v18 offset0:130 offset1:195
	ds_read2_b32 v[84:85], v19 offset1:65
	ds_read2_b32 v[86:87], v19 offset0:130 offset1:195
	s_waitcnt lgkmcnt(0)
	v_cvt_pk_bf16_f32 v24, v24, v25
	v_cvt_pk_bf16_f32 v25, v26, v27
	v_cvt_pk_bf16_f32 v26, v84, v85
	v_cvt_pk_bf16_f32 v27, v86, v87
	global_store_dwordx4 v22, v[24:27], s[48:49]
	s_add_u32 s48, s48, 0x200000
	s_addc_u32 s49, s49, 0
	s_waitcnt vmcnt(6)
	v_mul_f32_e32 v52, v52, v9
	v_mul_f32_e32 v53, v53, v9
	v_mul_f32_e32 v54, v54, v9
	v_mul_f32_e32 v55, v55, v9
	v_mul_f32_e32 v56, v56, v10
	v_mul_f32_e32 v57, v57, v10
	v_mul_f32_e32 v58, v58, v10
	v_mul_f32_e32 v59, v59, v10
	ds_write2_b32 v12, v52, v53 offset1:1
	ds_write2_b32 v12, v54, v55 offset0:2 offset1:3
	ds_write2_b32 v13, v56, v57 offset1:1
	ds_write2_b32 v13, v58, v59 offset0:2 offset1:3
	s_waitcnt lgkmcnt(0)
	s_barrier
	ds_read2_b32 v[24:25], v16 offset1:65
	ds_read2_b32 v[26:27], v16 offset0:130 offset1:195
	ds_read2_b32 v[84:85], v17 offset1:65
	ds_read2_b32 v[86:87], v17 offset0:130 offset1:195
	s_waitcnt lgkmcnt(0)
	v_cvt_pk_bf16_f32 v24, v24, v25
	v_cvt_pk_bf16_f32 v25, v26, v27
	v_cvt_pk_bf16_f32 v26, v84, v85
	v_cvt_pk_bf16_f32 v27, v86, v87
	global_store_dwordx4 v22, v[24:27], s[48:49]
	s_add_u32 s48, s48, 0x200000
	s_addc_u32 s49, s49, 0
	s_waitcnt vmcnt(5)
	v_mul_f32_e32 v60, v60, v9
	v_mul_f32_e32 v61, v61, v9
	v_mul_f32_e32 v62, v62, v9
	v_mul_f32_e32 v63, v63, v9
	v_mul_f32_e32 v64, v64, v10
	v_mul_f32_e32 v65, v65, v10
	v_mul_f32_e32 v66, v66, v10
	v_mul_f32_e32 v67, v67, v10
	ds_write2_b32 v14, v60, v61 offset1:1
	ds_write2_b32 v14, v62, v63 offset0:2 offset1:3
	ds_write2_b32 v15, v64, v65 offset1:1
	ds_write2_b32 v15, v66, v67 offset0:2 offset1:3
	s_waitcnt lgkmcnt(0)
	s_barrier
	ds_read2_b32 v[24:25], v18 offset1:65
	ds_read2_b32 v[26:27], v18 offset0:130 offset1:195
	ds_read2_b32 v[84:85], v19 offset1:65
	ds_read2_b32 v[86:87], v19 offset0:130 offset1:195
	s_waitcnt lgkmcnt(0)
	v_cvt_pk_bf16_f32 v24, v24, v25
	v_cvt_pk_bf16_f32 v25, v26, v27
	v_cvt_pk_bf16_f32 v26, v84, v85
	v_cvt_pk_bf16_f32 v27, v86, v87
	global_store_dwordx4 v22, v[24:27], s[48:49]
	s_add_u32 s48, s48, 0x200000
	s_addc_u32 s49, s49, 0
	s_waitcnt vmcnt(4)
	v_mul_f32_e32 v68, v68, v9
	v_mul_f32_e32 v69, v69, v9
	v_mul_f32_e32 v70, v70, v9
	v_mul_f32_e32 v71, v71, v9
	v_mul_f32_e32 v72, v72, v10
	v_mul_f32_e32 v73, v73, v10
	v_mul_f32_e32 v74, v74, v10
	v_mul_f32_e32 v75, v75, v10
	ds_write2_b32 v12, v68, v69 offset1:1
	ds_write2_b32 v12, v70, v71 offset0:2 offset1:3
	ds_write2_b32 v13, v72, v73 offset1:1
	ds_write2_b32 v13, v74, v75 offset0:2 offset1:3
	s_waitcnt lgkmcnt(0)
	s_barrier
	ds_read2_b32 v[24:25], v16 offset1:65
	ds_read2_b32 v[26:27], v16 offset0:130 offset1:195
	ds_read2_b32 v[84:85], v17 offset1:65
	ds_read2_b32 v[86:87], v17 offset0:130 offset1:195
	s_waitcnt lgkmcnt(0)
	v_cvt_pk_bf16_f32 v24, v24, v25
	v_cvt_pk_bf16_f32 v25, v26, v27
	v_cvt_pk_bf16_f32 v26, v84, v85
	v_cvt_pk_bf16_f32 v27, v86, v87
	global_store_dwordx4 v22, v[24:27], s[48:49]
.Lwup_done:
	v_mov_b32_e32 v3, v214
